# FFN-in GEMM epilogue: per-row sum-of-squares partial loads software-pipelined one tile ahead into dead VGPRs (issued during the previous tile's epilogue)
# speedup vs baseline: 1.0037x; 1.0037x over previous
; #define PG8_STAGE(bufoff, gbase, voff) do { _Pragma("unroll") for (int _i = 0; _i < 2; ++_i) \
;         __builtin_amdgcn_global_load_lds((const unsigned*)((const char*)(gbase) + (voff)[_i]), (PG8_LAS unsigned*)(lds + (bufoff) + ldsw + _i * 8192), 16, 0, 0); } while (0)
; #define PG8_WAIT_V(n) asm volatile("s_waitcnt vmcnt(" #n ")" ::: "memory")
; #define PG8_BAR __builtin_amdgcn_s_barrier()
; __device__ __forceinline__ void rows_rstd8(const float* pss, int row0, int fq, float (&rs)[2][4]) {
;     ...
;     for (int k = 0; k < 8; ++k) p[k] = pss[(size_t)fq * PSS_M + row0 + (k >> 2) * HALF + (k & 3) * 16];
; template <class Epi, class Sched, bool ALIGN_EPI = false, bool SP2 = false>
; __device__ __forceinline__ void gemm_phase(PG8_LAS unsigned char* lds, const Gemm g, const Sched& S, const Epi& E) {
;     ...
;         PG8_STAGE(PG8_SB(0, 0), cB, voffB); PG8_STAGE(PG8_SB(0, 1), cB + hstep, voffB); PG8_STAGE(PG8_SA(0, 0), cA, voffA); PG8_STAGE(PG8_SA(0, 1), cA + hstep, voffA);
;         if (wr == 1) PG8_BAR;
;         PG8_WAIT_V(2); PG8_BAR;
;         PG8_STAGE(PG8_SB(1, 0), cB + kstep, voffB); PG8_STAGE(PG8_SA(1, 0), cA + kstep, voffA); PG8_STAGE(PG8_SB(1, 1), cB + hstep + kstep, voffB);
;         PG8_WAIT_V(6); PG8_BAR;
.LBB0_977:
	s_add_u32 s42, s46, 0x2000000
	v_bfe_u32 v34, v32, 4, 2
	s_addc_u32 s43, s47, 0
	v_and_b32_e32 v33, 15, v32
	v_lshlrev_b32_e32 v35, 4, v34
	v_lshlrev_b32_e32 v32, 2, v32
	s_lshl_b32 s41, s41, 5
	v_lshl_or_b32 v161, s44, 6, v33
	v_lshl_or_b32 v33, v33, 6, v35
	s_lshl_b32 s44, s44, 13
	v_and_b32_e32 v32, 32, v32
	s_and_b32 s41, s41, 0x60
	s_add_i32 m0, s49, 0x18000
	v_lshl_add_u64 v[24:25], v[24:25], 0, s[96:97]
	v_bitop3_b32 v35, v33, s44, v32 bitop3:0xde
	s_lshl_b32 s44, s41, 7
	s_waitcnt vmcnt(2)
	s_barrier
	global_load_lds_dwordx4 v[24:25], off
	v_lshl_add_u64 v[22:23], v[22:23], 0, s[96:97]
	s_add_i32 m0, s49, 0x1a000
	s_add_i32 s65, s49, 0x8000
	s_add_i32 s66, s49, 0xa000
	v_bitop3_b32 v163, v33, s44, v32 bitop3:0xde
	global_load_lds_dwordx4 v[22:23], off
	v_lshl_add_u64 v[18:19], v[18:19], 0, s[96:97]
	s_mov_b32 m0, s65
	s_add_u32 s44, s60, 0x40080
	global_load_lds_dwordx4 v[18:19], off
	v_lshl_add_u64 v[18:19], v[20:21], 0, s[96:97]
	s_mov_b32 m0, s66
	s_addc_u32 s45, s61, 0
	global_load_lds_dwordx4 v[18:19], off
	s_add_i32 m0, s49, 0x1c000
	v_lshl_add_u64 v[18:19], s[44:45], 0, v[0:1]
	global_load_lds_dwordx4 v[18:19], off
	v_lshl_add_u64 v[18:19], s[44:45], 0, v[146:147]
	s_add_i32 m0, s49, 0x1e000
	s_cmpk_lt_u32 s40, 0x100
	global_load_lds_dwordx4 v[18:19], off
	v_lshlrev_b32_e32 v18, 17, v34
	v_mov_b32_e32 v19, v1
	v_lshl_add_u64 v[18:19], s[46:47], 0, v[18:19]
	s_mov_b64 s[46:47], 0x1e00000
	v_lshl_add_u64 v[152:153], v[18:19], 0, s[46:47]
	v_lshlrev_b32_e32 v18, 14, v30
	v_and_b32_e32 v18, 0xffff8000, v18
	v_lshl_add_u32 v18, v29, 11, v18
	v_and_b32_e32 v19, 1, v30
	v_lshl_or_b32 v18, v19, 6, v18
	v_lshl_add_u32 v154, v31, 1, v18
	v_lshlrev_b32_e32 v18, 14, v26
	v_and_b32_e32 v18, 0xffff8000, v18
	s_waitcnt vmcnt(6)
	v_lshl_add_u32 v18, v27, 11, v18
	v_and_b32_e32 v19, 1, v26
	v_lshl_or_b32 v165, v34, 3, s41
	v_lshl_or_b32 v18, v19, 6, v18
	v_readlane_b32 s40, v254, 40
	s_cselect_b64 s[44:45], -1, 0
	v_mov_b32_e32 v155, v1
	v_lshl_add_u32 v156, v28, 1, v18
	v_mov_b32_e32 v157, v1
	s_mov_b32 s67, 0
	v_add_u32_e32 v167, 0, v35
	v_readlane_b32 s68, v254, 28
	s_mov_b32 s69, s40
	v_lshl_add_u32 v4, s69, 8, v161
	v_ashrrev_i32_e32 v5, 31, v4
	v_lshl_add_u64 v[4:5], v[4:5], 2, v[152:153]
	global_load_dword v6, v[4:5], off offset:704
	global_load_dword v7, v[4:5], off offset:640
	global_load_dword v8, v[4:5], off offset:576
	global_load_dword v9, v[4:5], off offset:512
	global_load_dword v10, v[4:5], off offset:192
	global_load_dword v11, v[4:5], off offset:128
	global_load_dword v12, v[4:5], off offset:64
	global_load_dword v13, v[4:5], off
	s_barrier
	v_readlane_b32 s41, v254, 41
	s_branch .LBB0_980

; __device__ __forceinline__ u32x4 pack8(const f32x4 a, const f32x4 b) { u32x4 w; w.x = cvt_pk_bf16(a[0], a[1]); w.y = cvt_pk_bf16(a[2], a[3]); w.z = cvt_pk_bf16(b[0], b[1]); w.w = cvt_pk_bf16(b[2], b[3]); return w; }
; __device__ __forceinline__ void rows_rstd8(const float* pss, int row0, int fq, float (&rs)[2][4]) {
;     float p[8], q[8];
; #pragma unroll
;     for (int k = 0; k < 8; ++k) p[k] = pss[(size_t)fq * PSS_M + row0 + (k >> 2) * HALF + (k & 3) * 16];
;     asm volatile("" : "+v"(p[0]), "+v"(p[1]), "+v"(p[2]), "+v"(p[3]), "+v"(p[4]), "+v"(p[5]), "+v"(p[6]), "+v"(p[7]));
; #pragma unroll
;     for (int k = 0; k < 8; ++k) q[k] = __shfl_xor(p[k], 16);
;     asm volatile("" : "+v"(q[0]), "+v"(q[1]), "+v"(q[2]), "+v"(q[3]), "+v"(q[4]), "+v"(q[5]), "+v"(q[6]), "+v"(q[7]));
; #pragma unroll
;     for (int k = 0; k < 8; ++k) p[k] += q[k];
; #pragma unroll
;     for (int k = 0; k < 8; ++k) q[k] = __shfl_xor(p[k], 32);
;     asm volatile("" : "+v"(q[0]), "+v"(q[1]), "+v"(q[2]), "+v"(q[3]), "+v"(q[4]), "+v"(q[5]), "+v"(q[6]), "+v"(q[7]));
; #pragma unroll
;     for (int k = 0; k < 8; ++k) rs[k >> 2][k & 3] = __builtin_amdgcn_rsqf((p[k] + q[k]) * (1.0f / 1024.0f) + RMS_EPS);
; }
;     __device__ __forceinline__ void operator()(f32x4 (&acc)[2][2][4][2], const Unit& u, int wr, int wc, int fr, int fq) const {
;     ...
;         for (int ai = 0; ai < 2; ++ai)
; #pragma unroll
;             for (int m = 0; m < 4; ++m) {
;                 const int r = row0 + ai * HALF + m * 16; const float rstd = rs[ai][m]; f32x4 a[2];
; #pragma unroll
;                 for (int n = 0; n < 2; ++n) { const f32x4 g = acc[ai][0][m][n] * rstd, uu = acc[ai][1][m][n] * rstd;
; #pragma unroll
;                     for (int i = 0; i < 4; ++i) a[n][i] = g[i] * __builtin_amdgcn_rcpf(1.0f + __builtin_amdgcn_exp2f(g[i] * -1.4426950408889634f)) * uu[i]; }
;                 *(u32x4*)(act + (size_t)r * 2816 + col0) = pack8(a[0], a[1]);
.LBB0_986:
	v_lshl_add_u32 v158, s69, 8, v161
	s_waitcnt vmcnt(0)
	v_mov_b32_e32 v159, v6
	v_mov_b32_e32 v160, v7
	v_mov_b32_e32 v162, v8
	v_mov_b32_e32 v164, v9
	v_mov_b32_e32 v166, v10
	v_mov_b32_e32 v170, v11
	v_mov_b32_e32 v171, v12
	v_mov_b32_e32 v168, v13
	v_lshl_or_b32 v174, s68, 7, v165
	s_movk_i32 s47, 0x1600
	s_cmp_lg_u64 s[40:41], 0
	s_cbranch_scc0 .Lmy_pss_skip
	v_lshl_add_u32 v4, s52, 8, v161
	v_ashrrev_i32_e32 v5, 31, v4
	v_lshl_add_u64 v[4:5], v[4:5], 2, v[152:153]
	global_load_dword v6, v[4:5], off offset:704
	global_load_dword v7, v[4:5], off offset:640
	global_load_dword v8, v[4:5], off offset:576
	global_load_dword v9, v[4:5], off offset:512
	global_load_dword v10, v[4:5], off offset:192
	global_load_dword v11, v[4:5], off offset:128
	global_load_dword v12, v[4:5], off offset:64
	global_load_dword v13, v[4:5], off
.Lmy_pss_skip:
	s_andn2_b64 vcc, exec, s[40:41]
	ds_bpermute_b32 v169, v220, v168
	ds_bpermute_b32 v172, v220, v171
	ds_bpermute_b32 v173, v220, v170
	ds_bpermute_b32 v175, v220, v166
	ds_bpermute_b32 v176, v220, v164
	ds_bpermute_b32 v177, v220, v162
	ds_bpermute_b32 v178, v220, v160
	ds_bpermute_b32 v179, v220, v159
	s_waitcnt lgkmcnt(0)
	s_nop 0
	v_add_f32_e32 v168, v168, v169
	v_add_f32_e32 v169, v171, v172
	v_add_f32_e32 v170, v170, v173
	v_add_f32_e32 v166, v166, v175
	v_add_f32_e32 v164, v164, v176
	v_add_f32_e32 v162, v162, v177
	v_add_f32_e32 v160, v160, v178
	v_add_f32_e32 v159, v159, v179
	ds_bpermute_b32 v171, v221, v168
	ds_bpermute_b32 v172, v221, v169
	ds_bpermute_b32 v173, v221, v170
	ds_bpermute_b32 v175, v221, v166
	ds_bpermute_b32 v177, v221, v164
	ds_bpermute_b32 v178, v221, v162
	ds_bpermute_b32 v179, v221, v160
	ds_bpermute_b32 v182, v221, v159
	s_waitcnt lgkmcnt(0)
	s_nop 0
	v_add_f32_e32 v168, v168, v171
	v_fmamk_f32 v168, v168, 0x3a800000, v214
	v_rsq_f32_e32 v176, v168
	v_add_f32_e32 v168, v169, v172
	v_fmamk_f32 v168, v168, 0x3a800000, v214
	v_rsq_f32_e32 v172, v168
	v_add_f32_e32 v168, v170, v173
	v_add_f32_e32 v166, v166, v175
	v_add_f32_e32 v164, v164, v177
	v_add_f32_e32 v162, v162, v178
	v_add_f32_e32 v160, v160, v179
	v_add_f32_e32 v159, v159, v182
	v_fmamk_f32 v168, v168, 0x3a800000, v214
	v_fmamk_f32 v166, v166, 0x3a800000, v214
	v_fmamk_f32 v164, v164, 0x3a800000, v214
	v_fmamk_f32 v162, v162, 0x3a800000, v214
	v_fmamk_f32 v160, v160, 0x3a800000, v214
	v_fmamk_f32 v159, v159, 0x3a800000, v214
	v_pk_mul_f32 v[142:143], v[142:143], v[176:177] op_sel_hi:[1,0]
	v_rsq_f32_e32 v170, v168
	v_rsq_f32_e32 v168, v166
	v_rsq_f32_e32 v166, v164
	v_rsq_f32_e32 v164, v162
	v_rsq_f32_e32 v162, v160
	v_rsq_f32_e32 v160, v159
	v_mul_f32_e32 v159, 0xbfb8aa3b, v142
	v_exp_f32_e32 v159, v159
	v_pk_mul_f32 v[134:135], v[134:135], v[176:177] op_sel_hi:[1,0]
	v_pk_mul_f32 v[136:137], v[136:137], v[176:177] op_sel_hi:[1,0]
	v_pk_mul_f32 v[138:139], v[138:139], v[176:177] op_sel_hi:[1,0]
	v_add_f32_e32 v159, 1.0, v159
	v_rcp_f32_e32 v178, v159
	v_mul_f32_e32 v159, 0xbfb8aa3b, v143
	v_exp_f32_e32 v159, v159
	v_pk_mul_f32 v[130:131], v[130:131], v[176:177] op_sel_hi:[1,0]
	v_pk_mul_f32 v[132:133], v[132:133], v[176:177] op_sel_hi:[1,0]
	v_ashrrev_i32_e32 v175, 31, v174
	v_add_f32_e32 v159, 1.0, v159
	v_rcp_f32_e32 v179, v159
	v_pk_mul_f32 v[126:127], v[126:127], v[172:173] op_sel_hi:[1,0]
	v_pk_mul_f32 v[122:123], v[122:123], v[172:173] op_sel_hi:[1,0]
	v_pk_mul_f32 v[124:125], v[124:125], v[172:173] op_sel_hi:[1,0]
	v_pk_mul_f32 v[142:143], v[142:143], v[178:179]
	v_pk_mul_f32 v[118:119], v[118:119], v[172:173] op_sel_hi:[1,0]
	v_pk_mul_f32 v[134:135], v[134:135], v[142:143]
	v_pk_mul_f32 v[142:143], v[144:145], v[176:177] op_sel_hi:[1,0]
	v_pk_mul_f32 v[114:115], v[114:115], v[172:173] op_sel_hi:[1,0]
	v_mul_f32_e32 v144, 0xbfb8aa3b, v142
	v_mul_f32_e32 v145, 0xbfb8aa3b, v143
	v_exp_f32_e32 v144, v144
	v_exp_f32_e32 v145, v145
	v_pk_mul_f32 v[116:117], v[116:117], v[172:173] op_sel_hi:[1,0]
	v_pk_mul_f32 v[110:111], v[110:111], v[170:171] op_sel_hi:[1,0]
	v_add_f32_e32 v144, 1.0, v144
	v_add_f32_e32 v145, 1.0, v145
	v_rcp_f32_e32 v144, v144
	v_rcp_f32_e32 v145, v145
	v_pk_mul_f32 v[106:107], v[106:107], v[170:171] op_sel_hi:[1,0]
	v_pk_mul_f32 v[108:109], v[108:109], v[170:171] op_sel_hi:[1,0]
	v_pk_mul_f32 v[102:103], v[102:103], v[170:171] op_sel_hi:[1,0]
	v_pk_mul_f32 v[142:143], v[142:143], v[144:145]
	v_pk_mul_f32 v[98:99], v[98:99], v[170:171] op_sel_hi:[1,0]
	v_pk_mul_f32 v[136:137], v[136:137], v[142:143]
	v_mul_f32_e32 v142, 0xbfb8aa3b, v138
	v_mul_f32_e32 v143, 0xbfb8aa3b, v139
	v_exp_f32_e32 v142, v142
	v_exp_f32_e32 v143, v143
	v_pk_mul_f32 v[100:101], v[100:101], v[170:171] op_sel_hi:[1,0]
	v_pk_mul_f32 v[94:95], v[94:95], v[168:169] op_sel_hi:[1,0]
	v_add_f32_e32 v142, 1.0, v142
	v_add_f32_e32 v143, 1.0, v143
	v_rcp_f32_e32 v142, v142
	v_rcp_f32_e32 v143, v143
	v_pk_mul_f32 v[90:91], v[90:91], v[168:169] op_sel_hi:[1,0]
	v_pk_mul_f32 v[92:93], v[92:93], v[168:169] op_sel_hi:[1,0]
	v_pk_mul_f32 v[86:87], v[86:87], v[168:169] op_sel_hi:[1,0]
	v_pk_mul_f32 v[138:139], v[138:139], v[142:143]
	v_pk_mul_f32 v[82:83], v[82:83], v[168:169] op_sel_hi:[1,0]
	v_pk_mul_f32 v[138:139], v[130:131], v[138:139]
	v_pk_mul_f32 v[130:131], v[140:141], v[176:177] op_sel_hi:[1,0]
	v_pk_mul_f32 v[84:85], v[84:85], v[168:169] op_sel_hi:[1,0]
	v_mul_f32_e32 v140, 0xbfb8aa3b, v130
	v_mul_f32_e32 v141, 0xbfb8aa3b, v131
	v_exp_f32_e32 v140, v140
	v_exp_f32_e32 v141, v141
	v_pk_mul_f32 v[78:79], v[78:79], v[166:167] op_sel_hi:[1,0]
	v_pk_mul_f32 v[74:75], v[74:75], v[166:167] op_sel_hi:[1,0]
	v_add_f32_e32 v140, 1.0, v140
	v_add_f32_e32 v141, 1.0, v141
	v_rcp_f32_e32 v140, v140
	v_rcp_f32_e32 v141, v141
; __device__ __forceinline__ u32x4 pack8(const f32x4 a, const f32x4 b) { u32x4 w; w.x = cvt_pk_bf16(a[0], a[1]); w.y = cvt_pk_bf16(a[2], a[3]); w.z = cvt_pk_bf16(b[0], b[1]); w.w = cvt_pk_bf16(b[2], b[3]); return w; }
;     __device__ __forceinline__ void operator()(f32x4 (&acc)[2][2][4][2], const Unit& u, int wr, int wc, int fr, int fq) const {
;     ...
;         for (int ai = 0; ai < 2; ++ai)
; #pragma unroll
;             for (int m = 0; m < 4; ++m) {
;                 const int r = row0 + ai * HALF + m * 16; const float rstd = rs[ai][m]; f32x4 a[2];
; #pragma unroll
;                 for (int n = 0; n < 2; ++n) { const f32x4 g = acc[ai][0][m][n] * rstd, uu = acc[ai][1][m][n] * rstd;
; #pragma unroll
;                     for (int i = 0; i < 4; ++i) a[n][i] = g[i] * __builtin_amdgcn_rcpf(1.0f + __builtin_amdgcn_exp2f(g[i] * -1.4426950408889634f)) * uu[i]; }
;                 *(u32x4*)(act + (size_t)r * 2816 + col0) = pack8(a[0], a[1]);
	v_pk_mul_f32 v[76:77], v[76:77], v[166:167] op_sel_hi:[1,0]
	v_pk_mul_f32 v[70:71], v[70:71], v[166:167] op_sel_hi:[1,0]
	v_pk_mul_f32 v[66:67], v[66:67], v[166:167] op_sel_hi:[1,0]
	v_pk_mul_f32 v[130:131], v[130:131], v[140:141]
	v_pk_mul_f32 v[68:69], v[68:69], v[166:167] op_sel_hi:[1,0]
	v_pk_mul_f32 v[140:141], v[132:133], v[130:131]
	v_cvt_pk_bf16_f32 v130, v134, v135
	v_mov_b64_e32 v[134:135], s[42:43]
	v_cvt_pk_bf16_f32 v131, v136, v137
	v_cvt_pk_bf16_f32 v132, v138, v139
	v_mad_i64_i32 v[138:139], s[58:59], v158, s47, v[134:135]
	v_lshlrev_b64 v[136:137], 1, v[174:175]
	v_cvt_pk_bf16_f32 v133, v140, v141
	v_lshl_add_u64 v[138:139], v[138:139], 0, v[136:137]
	global_store_dwordx4 v[138:139], v[130:133], off
	v_pk_mul_f32 v[62:63], v[62:63], v[164:165] op_sel_hi:[1,0]
	v_pk_mul_f32 v[58:59], v[58:59], v[164:165] op_sel_hi:[1,0]
	v_mul_f32_e32 v130, 0xbfb8aa3b, v126
	v_mul_f32_e32 v131, 0xbfb8aa3b, v127
	v_exp_f32_e32 v130, v130
	v_exp_f32_e32 v131, v131
	v_pk_mul_f32 v[60:61], v[60:61], v[164:165] op_sel_hi:[1,0]
	v_pk_mul_f32 v[54:55], v[54:55], v[164:165] op_sel_hi:[1,0]
	v_add_f32_e32 v130, 1.0, v130
	v_add_f32_e32 v131, 1.0, v131
	v_rcp_f32_e32 v130, v130
	v_rcp_f32_e32 v131, v131
	v_pk_mul_f32 v[50:51], v[50:51], v[164:165] op_sel_hi:[1,0]
	v_pk_mul_f32 v[52:53], v[52:53], v[164:165] op_sel_hi:[1,0]
	v_pk_mul_f32 v[46:47], v[46:47], v[162:163] op_sel_hi:[1,0]
	v_pk_mul_f32 v[126:127], v[126:127], v[130:131]
	v_pk_mul_f32 v[42:43], v[42:43], v[162:163] op_sel_hi:[1,0]
	v_pk_mul_f32 v[122:123], v[122:123], v[126:127]
	v_pk_mul_f32 v[126:127], v[128:129], v[172:173] op_sel_hi:[1,0]
	v_pk_mul_f32 v[44:45], v[44:45], v[162:163] op_sel_hi:[1,0]
	v_mul_f32_e32 v128, 0xbfb8aa3b, v126
	v_mul_f32_e32 v129, 0xbfb8aa3b, v127
	v_exp_f32_e32 v128, v128
	v_exp_f32_e32 v129, v129
	v_pk_mul_f32 v[38:39], v[38:39], v[162:163] op_sel_hi:[1,0]
	v_pk_mul_f32 v[34:35], v[34:35], v[162:163] op_sel_hi:[1,0]
	v_add_f32_e32 v128, 1.0, v128
	v_add_f32_e32 v129, 1.0, v129
	v_rcp_f32_e32 v128, v128
	v_rcp_f32_e32 v129, v129
	v_pk_mul_f32 v[36:37], v[36:37], v[162:163] op_sel_hi:[1,0]
	v_pk_mul_f32 v[30:31], v[30:31], v[160:161] op_sel_hi:[1,0]
	v_pk_mul_f32 v[26:27], v[26:27], v[160:161] op_sel_hi:[1,0]
	v_pk_mul_f32 v[126:127], v[126:127], v[128:129]
	v_pk_mul_f32 v[28:29], v[28:29], v[160:161] op_sel_hi:[1,0]
	v_pk_mul_f32 v[124:125], v[124:125], v[126:127]
	v_mul_f32_e32 v126, 0xbfb8aa3b, v118
	v_mul_f32_e32 v127, 0xbfb8aa3b, v119
	v_exp_f32_e32 v126, v126
	v_exp_f32_e32 v127, v127
	v_pk_mul_f32 v[22:23], v[22:23], v[160:161] op_sel_hi:[1,0]
	v_pk_mul_f32 v[18:19], v[18:19], v[160:161] op_sel_hi:[1,0]
	v_add_f32_e32 v126, 1.0, v126
	v_add_f32_e32 v127, 1.0, v127
	v_rcp_f32_e32 v126, v126
	v_rcp_f32_e32 v127, v127
	v_pk_mul_f32 v[20:21], v[20:21], v[160:161] op_sel_hi:[1,0]
	v_pk_mul_f32 v[118:119], v[118:119], v[126:127]
	s_nop 0
	v_pk_mul_f32 v[118:119], v[114:115], v[118:119]
	v_pk_mul_f32 v[114:115], v[120:121], v[172:173] op_sel_hi:[1,0]
	v_or_b32_e32 v126, 16, v158
	v_mul_f32_e32 v120, 0xbfb8aa3b, v114
	v_mul_f32_e32 v121, 0xbfb8aa3b, v115
	v_exp_f32_e32 v120, v120
	v_exp_f32_e32 v121, v121
	v_add_f32_e32 v120, 1.0, v120
	v_add_f32_e32 v121, 1.0, v121
	v_rcp_f32_e32 v120, v120
	v_rcp_f32_e32 v121, v121
	s_nop 0
	v_pk_mul_f32 v[114:115], v[114:115], v[120:121]
	s_nop 0
	v_pk_mul_f32 v[120:121], v[116:117], v[114:115]
	v_cvt_pk_bf16_f32 v116, v118, v119
	v_mad_i64_i32 v[118:119], s[58:59], v126, s47, v[134:135]
	v_cvt_pk_bf16_f32 v114, v122, v123
	v_cvt_pk_bf16_f32 v115, v124, v125
	v_cvt_pk_bf16_f32 v117, v120, v121
	v_lshl_add_u64 v[118:119], v[118:119], 0, v[136:137]
	global_store_dwordx4 v[118:119], v[114:117], off
	s_nop 1
	v_mul_f32_e32 v114, 0xbfb8aa3b, v110
	v_mul_f32_e32 v115, 0xbfb8aa3b, v111
	v_exp_f32_e32 v114, v114
	v_exp_f32_e32 v115, v115
	v_add_f32_e32 v114, 1.0, v114
	v_add_f32_e32 v115, 1.0, v115
	v_rcp_f32_e32 v114, v114
	v_rcp_f32_e32 v115, v115
	s_nop 0
	v_pk_mul_f32 v[110:111], v[110:111], v[114:115]
	s_nop 0
	v_pk_mul_f32 v[106:107], v[106:107], v[110:111]
	v_pk_mul_f32 v[110:111], v[112:113], v[170:171] op_sel_hi:[1,0]
	s_nop 0
	v_mul_f32_e32 v112, 0xbfb8aa3b, v110
	v_mul_f32_e32 v113, 0xbfb8aa3b, v111
	v_exp_f32_e32 v112, v112
	v_exp_f32_e32 v113, v113
	v_add_f32_e32 v112, 1.0, v112
	v_add_f32_e32 v113, 1.0, v113
	v_rcp_f32_e32 v112, v112
	v_rcp_f32_e32 v113, v113
	s_nop 0
	v_pk_mul_f32 v[110:111], v[110:111], v[112:113]
	s_nop 0
	v_pk_mul_f32 v[108:109], v[108:109], v[110:111]
	v_mul_f32_e32 v110, 0xbfb8aa3b, v102
	v_mul_f32_e32 v111, 0xbfb8aa3b, v103
	v_exp_f32_e32 v110, v110
	v_exp_f32_e32 v111, v111
	v_add_f32_e32 v110, 1.0, v110
	v_add_f32_e32 v111, 1.0, v111
	v_rcp_f32_e32 v110, v110
	v_rcp_f32_e32 v111, v111
	s_nop 0
	v_pk_mul_f32 v[102:103], v[102:103], v[110:111]
	s_nop 0
	v_pk_mul_f32 v[102:103], v[98:99], v[102:103]
	v_pk_mul_f32 v[98:99], v[104:105], v[170:171] op_sel_hi:[1,0]
	v_or_b32_e32 v110, 32, v158
	v_mul_f32_e32 v104, 0xbfb8aa3b, v98
	v_mul_f32_e32 v105, 0xbfb8aa3b, v99
	v_exp_f32_e32 v104, v104
	v_exp_f32_e32 v105, v105
	v_add_f32_e32 v104, 1.0, v104
	v_add_f32_e32 v105, 1.0, v105
	v_rcp_f32_e32 v104, v104
	v_rcp_f32_e32 v105, v105
	s_nop 0
	v_pk_mul_f32 v[98:99], v[98:99], v[104:105]
	s_nop 0
	v_pk_mul_f32 v[104:105], v[100:101], v[98:99]
	v_cvt_pk_bf16_f32 v100, v102, v103
	v_mad_i64_i32 v[102:103], s[58:59], v110, s47, v[134:135]
	v_cvt_pk_bf16_f32 v98, v106, v107
	v_cvt_pk_bf16_f32 v99, v108, v109
	v_cvt_pk_bf16_f32 v101, v104, v105
	v_lshl_add_u64 v[102:103], v[102:103], 0, v[136:137]
	global_store_dwordx4 v[102:103], v[98:101], off
	s_nop 1
	v_mul_f32_e32 v98, 0xbfb8aa3b, v94
; __device__ __forceinline__ u32x4 pack8(const f32x4 a, const f32x4 b) { u32x4 w; w.x = cvt_pk_bf16(a[0], a[1]); w.y = cvt_pk_bf16(a[2], a[3]); w.z = cvt_pk_bf16(b[0], b[1]); w.w = cvt_pk_bf16(b[2], b[3]); return w; }
;     __device__ __forceinline__ void operator()(f32x4 (&acc)[2][2][4][2], const Unit& u, int wr, int wc, int fr, int fq) const {
;     ...
;         for (int ai = 0; ai < 2; ++ai)
; #pragma unroll
;             for (int m = 0; m < 4; ++m) {
;                 const int r = row0 + ai * HALF + m * 16; const float rstd = rs[ai][m]; f32x4 a[2];
; #pragma unroll
;                 for (int n = 0; n < 2; ++n) { const f32x4 g = acc[ai][0][m][n] * rstd, uu = acc[ai][1][m][n] * rstd;
; #pragma unroll
;                     for (int i = 0; i < 4; ++i) a[n][i] = g[i] * __builtin_amdgcn_rcpf(1.0f + __builtin_amdgcn_exp2f(g[i] * -1.4426950408889634f)) * uu[i]; }
;                 *(u32x4*)(act + (size_t)r * 2816 + col0) = pack8(a[0], a[1]);
	v_mul_f32_e32 v99, 0xbfb8aa3b, v95
	v_exp_f32_e32 v98, v98
	v_exp_f32_e32 v99, v99
	v_add_f32_e32 v98, 1.0, v98
	v_add_f32_e32 v99, 1.0, v99
	v_rcp_f32_e32 v98, v98
	v_rcp_f32_e32 v99, v99
	s_nop 0
	v_pk_mul_f32 v[94:95], v[94:95], v[98:99]
	s_nop 0
	v_pk_mul_f32 v[90:91], v[90:91], v[94:95]
	v_pk_mul_f32 v[94:95], v[96:97], v[168:169] op_sel_hi:[1,0]
	s_nop 0
	v_mul_f32_e32 v96, 0xbfb8aa3b, v94
	v_mul_f32_e32 v97, 0xbfb8aa3b, v95
	v_exp_f32_e32 v96, v96
	v_exp_f32_e32 v97, v97
	v_add_f32_e32 v96, 1.0, v96
	v_add_f32_e32 v97, 1.0, v97
	v_rcp_f32_e32 v96, v96
	v_rcp_f32_e32 v97, v97
	s_nop 0
	v_pk_mul_f32 v[94:95], v[94:95], v[96:97]
	s_nop 0
	v_pk_mul_f32 v[92:93], v[92:93], v[94:95]
	v_mul_f32_e32 v94, 0xbfb8aa3b, v86
	v_mul_f32_e32 v95, 0xbfb8aa3b, v87
	v_exp_f32_e32 v94, v94
	v_exp_f32_e32 v95, v95
	v_add_f32_e32 v94, 1.0, v94
	v_add_f32_e32 v95, 1.0, v95
	v_rcp_f32_e32 v94, v94
	v_rcp_f32_e32 v95, v95
	s_nop 0
	v_pk_mul_f32 v[86:87], v[86:87], v[94:95]
	s_nop 0
	v_pk_mul_f32 v[86:87], v[82:83], v[86:87]
	v_pk_mul_f32 v[82:83], v[88:89], v[168:169] op_sel_hi:[1,0]
	v_or_b32_e32 v94, 48, v158
	v_mul_f32_e32 v88, 0xbfb8aa3b, v82
	v_mul_f32_e32 v89, 0xbfb8aa3b, v83
	v_exp_f32_e32 v88, v88
	v_exp_f32_e32 v89, v89
	v_add_f32_e32 v88, 1.0, v88
	v_add_f32_e32 v89, 1.0, v89
	v_rcp_f32_e32 v88, v88
	v_rcp_f32_e32 v89, v89
	s_nop 0
	v_pk_mul_f32 v[82:83], v[82:83], v[88:89]
	s_nop 0
	v_pk_mul_f32 v[88:89], v[84:85], v[82:83]
	v_cvt_pk_bf16_f32 v84, v86, v87
	v_mad_i64_i32 v[86:87], s[58:59], v94, s47, v[134:135]
	v_cvt_pk_bf16_f32 v82, v90, v91
	v_cvt_pk_bf16_f32 v83, v92, v93
	v_cvt_pk_bf16_f32 v85, v88, v89
	v_lshl_add_u64 v[86:87], v[86:87], 0, v[136:137]
	global_store_dwordx4 v[86:87], v[82:85], off
	s_nop 1
	v_mul_f32_e32 v82, 0xbfb8aa3b, v78
	v_mul_f32_e32 v83, 0xbfb8aa3b, v79
	v_exp_f32_e32 v82, v82
	v_exp_f32_e32 v83, v83
	v_add_u32_e32 v84, 0x80, v158
	v_add_f32_e32 v82, 1.0, v82
	v_add_f32_e32 v83, 1.0, v83
	v_rcp_f32_e32 v82, v82
	v_rcp_f32_e32 v83, v83
	s_nop 0
	v_pk_mul_f32 v[78:79], v[78:79], v[82:83]
	s_nop 0
	v_pk_mul_f32 v[74:75], v[74:75], v[78:79]
	v_pk_mul_f32 v[78:79], v[80:81], v[166:167] op_sel_hi:[1,0]
	s_nop 0
	v_mul_f32_e32 v80, 0xbfb8aa3b, v78
	v_mul_f32_e32 v81, 0xbfb8aa3b, v79
	v_exp_f32_e32 v80, v80
	v_exp_f32_e32 v81, v81
	v_add_f32_e32 v80, 1.0, v80
	v_add_f32_e32 v81, 1.0, v81
	v_rcp_f32_e32 v80, v80
	v_rcp_f32_e32 v81, v81
	s_nop 0
	v_pk_mul_f32 v[78:79], v[78:79], v[80:81]
	s_nop 0
	v_pk_mul_f32 v[76:77], v[76:77], v[78:79]
	v_mul_f32_e32 v78, 0xbfb8aa3b, v70
	v_mul_f32_e32 v79, 0xbfb8aa3b, v71
	v_exp_f32_e32 v78, v78
	v_exp_f32_e32 v79, v79
	v_add_f32_e32 v78, 1.0, v78
	v_add_f32_e32 v79, 1.0, v79
	v_rcp_f32_e32 v78, v78
	v_rcp_f32_e32 v79, v79
	s_nop 0
	v_pk_mul_f32 v[70:71], v[70:71], v[78:79]
	s_nop 0
	v_pk_mul_f32 v[70:71], v[66:67], v[70:71]
	v_pk_mul_f32 v[66:67], v[72:73], v[166:167] op_sel_hi:[1,0]
	s_nop 0
	v_mul_f32_e32 v72, 0xbfb8aa3b, v66
	v_mul_f32_e32 v73, 0xbfb8aa3b, v67
	v_exp_f32_e32 v72, v72
	v_exp_f32_e32 v73, v73
	v_add_f32_e32 v72, 1.0, v72
	v_add_f32_e32 v73, 1.0, v73
	v_rcp_f32_e32 v72, v72
	v_rcp_f32_e32 v73, v73
	s_nop 0
	v_pk_mul_f32 v[66:67], v[66:67], v[72:73]
	s_nop 0
	v_pk_mul_f32 v[72:73], v[68:69], v[66:67]
	v_cvt_pk_bf16_f32 v68, v70, v71
	v_mad_i64_i32 v[70:71], s[58:59], v84, s47, v[134:135]
	v_cvt_pk_bf16_f32 v66, v74, v75
	v_cvt_pk_bf16_f32 v67, v76, v77
	v_cvt_pk_bf16_f32 v69, v72, v73
	v_lshl_add_u64 v[70:71], v[70:71], 0, v[136:137]
	global_store_dwordx4 v[70:71], v[66:69], off
	s_nop 1
	v_mul_f32_e32 v66, 0xbfb8aa3b, v62
	v_mul_f32_e32 v67, 0xbfb8aa3b, v63
	v_exp_f32_e32 v66, v66
	v_exp_f32_e32 v67, v67
	v_add_f32_e32 v66, 1.0, v66
	v_add_f32_e32 v67, 1.0, v67
	v_rcp_f32_e32 v66, v66
	v_rcp_f32_e32 v67, v67
	s_nop 0
	v_pk_mul_f32 v[62:63], v[62:63], v[66:67]
	s_nop 0
	v_pk_mul_f32 v[58:59], v[58:59], v[62:63]
	v_pk_mul_f32 v[62:63], v[64:65], v[164:165] op_sel_hi:[1,0]
	s_nop 0
	v_mul_f32_e32 v64, 0xbfb8aa3b, v62
	v_mul_f32_e32 v65, 0xbfb8aa3b, v63
	v_exp_f32_e32 v64, v64
	v_exp_f32_e32 v65, v65
	v_add_f32_e32 v64, 1.0, v64
	v_add_f32_e32 v65, 1.0, v65
	v_rcp_f32_e32 v64, v64
	v_rcp_f32_e32 v65, v65
	s_nop 0
	v_pk_mul_f32 v[62:63], v[62:63], v[64:65]
	s_nop 0
	v_pk_mul_f32 v[60:61], v[60:61], v[62:63]
	v_mul_f32_e32 v62, 0xbfb8aa3b, v54
	v_mul_f32_e32 v63, 0xbfb8aa3b, v55
	v_exp_f32_e32 v62, v62
	v_exp_f32_e32 v63, v63
	v_add_f32_e32 v62, 1.0, v62
	v_add_f32_e32 v63, 1.0, v63
	v_rcp_f32_e32 v62, v62
	v_rcp_f32_e32 v63, v63
	s_nop 0
; __device__ __forceinline__ u32x4 pack8(const f32x4 a, const f32x4 b) { u32x4 w; w.x = cvt_pk_bf16(a[0], a[1]); w.y = cvt_pk_bf16(a[2], a[3]); w.z = cvt_pk_bf16(b[0], b[1]); w.w = cvt_pk_bf16(b[2], b[3]); return w; }
;     __device__ __forceinline__ void operator()(f32x4 (&acc)[2][2][4][2], const Unit& u, int wr, int wc, int fr, int fq) const {
;     ...
;         for (int ai = 0; ai < 2; ++ai)
; #pragma unroll
;             for (int m = 0; m < 4; ++m) {
;                 const int r = row0 + ai * HALF + m * 16; const float rstd = rs[ai][m]; f32x4 a[2];
; #pragma unroll
;                 for (int n = 0; n < 2; ++n) { const f32x4 g = acc[ai][0][m][n] * rstd, uu = acc[ai][1][m][n] * rstd;
; #pragma unroll
;                     for (int i = 0; i < 4; ++i) a[n][i] = g[i] * __builtin_amdgcn_rcpf(1.0f + __builtin_amdgcn_exp2f(g[i] * -1.4426950408889634f)) * uu[i]; }
;                 *(u32x4*)(act + (size_t)r * 2816 + col0) = pack8(a[0], a[1]);
	v_pk_mul_f32 v[54:55], v[54:55], v[62:63]
	s_nop 0
	v_pk_mul_f32 v[54:55], v[50:51], v[54:55]
	v_pk_mul_f32 v[50:51], v[56:57], v[164:165] op_sel_hi:[1,0]
	v_add_u32_e32 v62, 0x90, v158
	v_mul_f32_e32 v56, 0xbfb8aa3b, v50
	v_mul_f32_e32 v57, 0xbfb8aa3b, v51
	v_exp_f32_e32 v56, v56
	v_exp_f32_e32 v57, v57
	v_add_f32_e32 v56, 1.0, v56
	v_add_f32_e32 v57, 1.0, v57
	v_rcp_f32_e32 v56, v56
	v_rcp_f32_e32 v57, v57
	s_nop 0
	v_pk_mul_f32 v[50:51], v[50:51], v[56:57]
	s_nop 0
	v_pk_mul_f32 v[56:57], v[52:53], v[50:51]
	v_cvt_pk_bf16_f32 v52, v54, v55
	v_mad_i64_i32 v[54:55], s[58:59], v62, s47, v[134:135]
	v_cvt_pk_bf16_f32 v50, v58, v59
	v_cvt_pk_bf16_f32 v51, v60, v61
	v_cvt_pk_bf16_f32 v53, v56, v57
	v_lshl_add_u64 v[54:55], v[54:55], 0, v[136:137]
	global_store_dwordx4 v[54:55], v[50:53], off
	s_nop 1
	v_mul_f32_e32 v50, 0xbfb8aa3b, v46
	v_mul_f32_e32 v51, 0xbfb8aa3b, v47
	v_exp_f32_e32 v50, v50
	v_exp_f32_e32 v51, v51
	v_add_f32_e32 v50, 1.0, v50
	v_add_f32_e32 v51, 1.0, v51
	v_rcp_f32_e32 v50, v50
	v_rcp_f32_e32 v51, v51
	s_nop 0
	v_pk_mul_f32 v[46:47], v[46:47], v[50:51]
	s_nop 0
	v_pk_mul_f32 v[42:43], v[42:43], v[46:47]
	v_pk_mul_f32 v[46:47], v[48:49], v[162:163] op_sel_hi:[1,0]
	s_nop 0
	v_mul_f32_e32 v48, 0xbfb8aa3b, v46
	v_mul_f32_e32 v49, 0xbfb8aa3b, v47
	v_exp_f32_e32 v48, v48
	v_exp_f32_e32 v49, v49
	v_add_f32_e32 v48, 1.0, v48
	v_add_f32_e32 v49, 1.0, v49
	v_rcp_f32_e32 v48, v48
	v_rcp_f32_e32 v49, v49
	s_nop 0
	v_pk_mul_f32 v[46:47], v[46:47], v[48:49]
	s_nop 0
	v_pk_mul_f32 v[44:45], v[44:45], v[46:47]
	v_mul_f32_e32 v46, 0xbfb8aa3b, v38
	v_mul_f32_e32 v47, 0xbfb8aa3b, v39
	v_exp_f32_e32 v46, v46
	v_exp_f32_e32 v47, v47
	v_add_f32_e32 v46, 1.0, v46
	v_add_f32_e32 v47, 1.0, v47
	v_rcp_f32_e32 v46, v46
	v_rcp_f32_e32 v47, v47
	s_nop 0
	v_pk_mul_f32 v[38:39], v[38:39], v[46:47]
	s_nop 0
	v_pk_mul_f32 v[38:39], v[34:35], v[38:39]
	v_pk_mul_f32 v[34:35], v[40:41], v[162:163] op_sel_hi:[1,0]
	v_add_u32_e32 v46, 0xa0, v158
	v_mul_f32_e32 v40, 0xbfb8aa3b, v34
	v_mul_f32_e32 v41, 0xbfb8aa3b, v35
	v_exp_f32_e32 v40, v40
	v_exp_f32_e32 v41, v41
	v_add_f32_e32 v40, 1.0, v40
	v_add_f32_e32 v41, 1.0, v41
	v_rcp_f32_e32 v40, v40
	v_rcp_f32_e32 v41, v41
	s_nop 0
	v_pk_mul_f32 v[34:35], v[34:35], v[40:41]
	s_nop 0
	v_pk_mul_f32 v[40:41], v[36:37], v[34:35]
	v_cvt_pk_bf16_f32 v36, v38, v39
	v_mad_i64_i32 v[38:39], s[58:59], v46, s47, v[134:135]
	v_cvt_pk_bf16_f32 v34, v42, v43
	v_cvt_pk_bf16_f32 v35, v44, v45
	v_cvt_pk_bf16_f32 v37, v40, v41
	v_lshl_add_u64 v[38:39], v[38:39], 0, v[136:137]
	global_store_dwordx4 v[38:39], v[34:37], off
	s_nop 1
	v_mul_f32_e32 v34, 0xbfb8aa3b, v30
	v_mul_f32_e32 v35, 0xbfb8aa3b, v31
	v_exp_f32_e32 v34, v34
	v_exp_f32_e32 v35, v35
	v_add_f32_e32 v34, 1.0, v34
	v_add_f32_e32 v35, 1.0, v35
	v_rcp_f32_e32 v34, v34
	v_rcp_f32_e32 v35, v35
	s_nop 0
	v_pk_mul_f32 v[30:31], v[30:31], v[34:35]
	s_nop 0
	v_pk_mul_f32 v[26:27], v[26:27], v[30:31]
	v_pk_mul_f32 v[30:31], v[32:33], v[160:161] op_sel_hi:[1,0]
	s_nop 0
	v_mul_f32_e32 v32, 0xbfb8aa3b, v30
	v_mul_f32_e32 v33, 0xbfb8aa3b, v31
	v_exp_f32_e32 v32, v32
	v_exp_f32_e32 v33, v33
	v_add_f32_e32 v32, 1.0, v32
	v_add_f32_e32 v33, 1.0, v33
	v_rcp_f32_e32 v32, v32
	v_rcp_f32_e32 v33, v33
	s_nop 0
	v_pk_mul_f32 v[30:31], v[30:31], v[32:33]
	s_nop 0
	v_pk_mul_f32 v[28:29], v[28:29], v[30:31]
	v_mul_f32_e32 v30, 0xbfb8aa3b, v22
	v_mul_f32_e32 v31, 0xbfb8aa3b, v23
	v_exp_f32_e32 v30, v30
	v_exp_f32_e32 v31, v31
	v_add_f32_e32 v30, 1.0, v30
	v_add_f32_e32 v31, 1.0, v31
	v_rcp_f32_e32 v30, v30
	v_rcp_f32_e32 v31, v31
	s_nop 0
	v_pk_mul_f32 v[22:23], v[22:23], v[30:31]
	s_nop 0
	v_pk_mul_f32 v[22:23], v[18:19], v[22:23]
	v_pk_mul_f32 v[18:19], v[24:25], v[160:161] op_sel_hi:[1,0]
	v_add_u32_e32 v30, 0xb0, v158
	v_mul_f32_e32 v24, 0xbfb8aa3b, v18
	v_mul_f32_e32 v25, 0xbfb8aa3b, v19
	v_exp_f32_e32 v24, v24
	v_exp_f32_e32 v25, v25
	v_add_f32_e32 v24, 1.0, v24
	v_add_f32_e32 v25, 1.0, v25
	v_rcp_f32_e32 v24, v24
	v_rcp_f32_e32 v25, v25
	s_nop 0
	v_pk_mul_f32 v[18:19], v[18:19], v[24:25]
	s_nop 0
	v_pk_mul_f32 v[24:25], v[20:21], v[18:19]
	v_cvt_pk_bf16_f32 v20, v22, v23
	v_mad_i64_i32 v[22:23], s[58:59], v30, s47, v[134:135]
	v_cvt_pk_bf16_f32 v18, v26, v27
	v_cvt_pk_bf16_f32 v19, v28, v29
	v_cvt_pk_bf16_f32 v21, v24, v25
	v_lshl_add_u64 v[22:23], v[22:23], 0, v[136:137]
	s_mov_b64 s[58:59], -1
	global_store_dwordx4 v[22:23], v[18:21], off
	s_cbranch_vccnz .LBB0_979
	s_andn2_b64 vcc, exec, s[38:39]
	s_cbranch_vccnz .LBB0_978
	s_barrier
	s_branch .LBB0_978
